# GEMM K-loop heads placed at 4 mod 8 bytes (.p2align 3 + s_nop before each loop label)
# speedup vs baseline: 1.0077x; 1.0077x over previous
.LBB0_162:
	s_ashr_i32 s19, s18, 31
	s_lshl_b64 s[20:21], s[18:19], 19
	s_add_u32 s20, s8, s20
	s_addc_u32 s21, s9, s21
	s_and_b64 s[22:23], s[4:5], exec
	s_cselect_b32 s19, s21, s27
	s_cselect_b32 s51, s20, s26
	s_ashr_i32 s17, s16, 31
	s_lshl_b64 s[22:23], s[16:17], 19
	s_add_u32 s22, s31, s22
	s_addc_u32 s23, s34, s23
	s_and_b64 s[28:29], s[4:5], exec
	s_cselect_b32 s17, s23, s25
	s_cselect_b32 s52, s22, s24
	s_add_u32 s53, s24, 0x100
	s_addc_u32 s54, s25, 0
	s_add_u32 s24, s26, 0x40080
	v_mov_b32_e32 v0, 0
	s_addc_u32 s25, s27, 0
	s_mov_b32 s55, -2
	v_mov_b32_e32 v1, v0
	v_mov_b32_e32 v2, v0
	v_mov_b32_e32 v3, v0
	v_mov_b32_e32 v4, v0
	v_mov_b32_e32 v5, v0
	v_mov_b32_e32 v6, v0
	v_mov_b32_e32 v7, v0
	v_mov_b32_e32 v16, v0
	v_mov_b32_e32 v17, v0
	s_waitcnt vmcnt(0)
	v_mov_b32_e32 v18, v0
	v_mov_b32_e32 v19, v0
	v_mov_b32_e32 v20, v0
	v_mov_b32_e32 v21, v0
	v_mov_b32_e32 v22, v0
	v_mov_b32_e32 v23, v0
	v_mov_b32_e32 v32, v0
	v_mov_b32_e32 v33, v0
	v_mov_b32_e32 v34, v0
	v_mov_b32_e32 v35, v0
	v_mov_b32_e32 v36, v0
	v_mov_b32_e32 v37, v0
	v_mov_b32_e32 v38, v0
	v_mov_b32_e32 v39, v0
	v_mov_b32_e32 v48, v0
	v_mov_b32_e32 v49, v0
	v_mov_b32_e32 v50, v0
	v_mov_b32_e32 v51, v0
	v_mov_b32_e32 v52, v0
	v_mov_b32_e32 v53, v0
	v_mov_b32_e32 v54, v0
	v_mov_b32_e32 v55, v0
	v_mov_b32_e32 v8, v0
	v_mov_b32_e32 v9, v0
	v_mov_b32_e32 v10, v0
	v_mov_b32_e32 v11, v0
	v_mov_b32_e32 v12, v0
	v_mov_b32_e32 v13, v0
	v_mov_b32_e32 v14, v0
	v_mov_b32_e32 v15, v0
	v_mov_b32_e32 v24, v0
	v_mov_b32_e32 v25, v0
	v_mov_b32_e32 v26, v0
	v_mov_b32_e32 v27, v0
	v_mov_b32_e32 v28, v0
	v_mov_b32_e32 v29, v0
	v_mov_b32_e32 v30, v0
	v_mov_b32_e32 v31, v0
	v_mov_b32_e32 v40, v0
	v_mov_b32_e32 v41, v0
	v_mov_b32_e32 v42, v0
	v_mov_b32_e32 v43, v0
	v_mov_b32_e32 v44, v0
	v_mov_b32_e32 v45, v0
	v_mov_b32_e32 v46, v0
	v_mov_b32_e32 v47, v0
	v_mov_b32_e32 v56, v0
	v_mov_b32_e32 v57, v0
	v_mov_b32_e32 v58, v0
	v_mov_b32_e32 v59, v0
	v_mov_b32_e32 v60, v0
	v_mov_b32_e32 v61, v0
	v_mov_b32_e32 v62, v0
	v_mov_b32_e32 v63, v0
	v_mov_b32_e32 v64, v0
	v_mov_b32_e32 v65, v0
	v_mov_b32_e32 v66, v0
	v_mov_b32_e32 v67, v0
	v_mov_b32_e32 v68, v0
	v_mov_b32_e32 v69, v0
	v_mov_b32_e32 v70, v0
	v_mov_b32_e32 v71, v0
	v_mov_b32_e32 v80, v0
	v_mov_b32_e32 v81, v0
	v_mov_b32_e32 v82, v0
	v_mov_b32_e32 v83, v0
	v_mov_b32_e32 v84, v0
	v_mov_b32_e32 v85, v0
	v_mov_b32_e32 v86, v0
	v_mov_b32_e32 v87, v0
	v_mov_b32_e32 v96, v0
	v_mov_b32_e32 v97, v0
	v_mov_b32_e32 v98, v0
	v_mov_b32_e32 v99, v0
	v_mov_b32_e32 v100, v0
	v_mov_b32_e32 v101, v0
	v_mov_b32_e32 v102, v0
	v_mov_b32_e32 v103, v0
	v_mov_b32_e32 v112, v0
	v_mov_b32_e32 v113, v0
	v_mov_b32_e32 v114, v0
	v_mov_b32_e32 v115, v0
	v_mov_b32_e32 v116, v0
	v_mov_b32_e32 v117, v0
	v_mov_b32_e32 v118, v0
	v_mov_b32_e32 v119, v0
	v_mov_b32_e32 v72, v0
	v_mov_b32_e32 v73, v0
	v_mov_b32_e32 v74, v0
	v_mov_b32_e32 v75, v0
	v_mov_b32_e32 v76, v0
	v_mov_b32_e32 v77, v0
	v_mov_b32_e32 v78, v0
	v_mov_b32_e32 v79, v0
	v_mov_b32_e32 v88, v0
	v_mov_b32_e32 v89, v0
	v_mov_b32_e32 v90, v0
	v_mov_b32_e32 v91, v0
	v_mov_b32_e32 v92, v0
	v_mov_b32_e32 v93, v0
	v_mov_b32_e32 v94, v0
	v_mov_b32_e32 v95, v0
	v_mov_b32_e32 v104, v0
	v_mov_b32_e32 v105, v0
	v_mov_b32_e32 v106, v0
	v_mov_b32_e32 v107, v0
	v_mov_b32_e32 v108, v0
	v_mov_b32_e32 v109, v0
	v_mov_b32_e32 v110, v0
	v_mov_b32_e32 v111, v0
	v_mov_b32_e32 v120, v0
	v_mov_b32_e32 v121, v0
	v_mov_b32_e32 v122, v0
	v_mov_b32_e32 v123, v0
	v_mov_b32_e32 v124, v0
	v_mov_b32_e32 v125, v0
	v_mov_b32_e32 v126, v0
	v_mov_b32_e32 v127, v0
	v_add_u32_e32 v204, 0x80, v128
	v_add_u32_e32 v205, 0x80, v130
	v_add_u32_e32 v220, 0x80, v132
	v_add_u32_e32 v221, 0x80, v134
	.p2align	3
	s_nop 0

.LBB0_605:
	s_ashr_i32 s21, s20, 31
	s_lshl_b64 s[22:23], s[20:21], 19
	s_add_u32 s22, s39, s22
	s_addc_u32 s23, s40, s23
	s_and_b64 s[24:25], s[6:7], exec
	s_cselect_b32 s21, s23, s29
	s_cselect_b32 s27, s22, s28
	s_ashr_i32 s19, s18, 31
	s_lshl_b64 s[24:25], s[18:19], 19
	s_add_u32 s24, s41, s24
	s_addc_u32 s25, s42, s25
	s_and_b64 s[34:35], s[6:7], exec
	s_cselect_b32 s19, s25, s31
	s_cselect_b32 s55, s24, s30
	s_add_u32 s56, s30, 0x100
	v_mov_b32_e32 v0, 0
	s_addc_u32 s57, s31, 0
	s_mov_b32 s58, -2
	v_mov_b32_e32 v1, v0
	v_mov_b32_e32 v2, v0
	v_mov_b32_e32 v3, v0
	v_mov_b32_e32 v4, v0
	v_mov_b32_e32 v5, v0
	v_mov_b32_e32 v6, v0
	v_mov_b32_e32 v7, v0
	v_mov_b32_e32 v16, v0
	v_mov_b32_e32 v17, v0
	v_mov_b32_e32 v18, v0
	v_mov_b32_e32 v19, v0
	v_mov_b32_e32 v20, v0
	v_mov_b32_e32 v21, v0
	v_mov_b32_e32 v22, v0
	v_mov_b32_e32 v23, v0
	v_mov_b32_e32 v32, v0
	v_mov_b32_e32 v33, v0
	v_mov_b32_e32 v34, v0
	v_mov_b32_e32 v35, v0
	v_mov_b32_e32 v36, v0
	v_mov_b32_e32 v37, v0
	v_mov_b32_e32 v38, v0
	v_mov_b32_e32 v39, v0
	v_mov_b32_e32 v48, v0
	v_mov_b32_e32 v49, v0
	v_mov_b32_e32 v50, v0
	v_mov_b32_e32 v51, v0
	v_mov_b32_e32 v52, v0
	v_mov_b32_e32 v53, v0
	v_mov_b32_e32 v54, v0
	v_mov_b32_e32 v55, v0
	v_mov_b32_e32 v8, v0
	v_mov_b32_e32 v9, v0
	v_mov_b32_e32 v10, v0
	v_mov_b32_e32 v11, v0
	v_mov_b32_e32 v12, v0
	v_mov_b32_e32 v13, v0
	v_mov_b32_e32 v14, v0
	v_mov_b32_e32 v15, v0
	v_mov_b32_e32 v24, v0
	v_mov_b32_e32 v25, v0
	v_mov_b32_e32 v26, v0
	v_mov_b32_e32 v27, v0
	v_mov_b32_e32 v28, v0
	v_mov_b32_e32 v29, v0
	v_mov_b32_e32 v30, v0
	v_mov_b32_e32 v31, v0
	v_mov_b32_e32 v40, v0
	v_mov_b32_e32 v41, v0
	v_mov_b32_e32 v42, v0
	v_mov_b32_e32 v43, v0
	v_mov_b32_e32 v44, v0
	v_mov_b32_e32 v45, v0
	v_mov_b32_e32 v46, v0
	v_mov_b32_e32 v47, v0
	v_mov_b32_e32 v56, v0
	v_mov_b32_e32 v57, v0
	v_mov_b32_e32 v58, v0
	v_mov_b32_e32 v59, v0
	v_mov_b32_e32 v60, v0
	v_mov_b32_e32 v61, v0
	v_mov_b32_e32 v62, v0
	v_mov_b32_e32 v63, v0
	v_mov_b32_e32 v64, v0
	v_mov_b32_e32 v65, v0
	v_mov_b32_e32 v66, v0
	v_mov_b32_e32 v67, v0
	v_mov_b32_e32 v68, v0
	v_mov_b32_e32 v69, v0
	v_mov_b32_e32 v70, v0
	v_mov_b32_e32 v71, v0
	v_mov_b32_e32 v80, v0
	v_mov_b32_e32 v81, v0
	v_mov_b32_e32 v82, v0
	v_mov_b32_e32 v83, v0
	v_mov_b32_e32 v84, v0
	v_mov_b32_e32 v85, v0
	v_mov_b32_e32 v86, v0
	v_mov_b32_e32 v87, v0
	v_mov_b32_e32 v96, v0
	v_mov_b32_e32 v97, v0
	v_mov_b32_e32 v98, v0
	v_mov_b32_e32 v99, v0
	v_mov_b32_e32 v100, v0
	v_mov_b32_e32 v101, v0
	v_mov_b32_e32 v102, v0
	v_mov_b32_e32 v103, v0
	v_mov_b32_e32 v112, v0
	v_mov_b32_e32 v113, v0
	v_mov_b32_e32 v114, v0
	v_mov_b32_e32 v115, v0
	v_mov_b32_e32 v116, v0
	v_mov_b32_e32 v117, v0
	v_mov_b32_e32 v118, v0
	v_mov_b32_e32 v119, v0
	v_mov_b32_e32 v72, v0
	v_mov_b32_e32 v73, v0
	v_mov_b32_e32 v74, v0
	v_mov_b32_e32 v75, v0
	v_mov_b32_e32 v76, v0
	v_mov_b32_e32 v77, v0
	v_mov_b32_e32 v78, v0
	v_mov_b32_e32 v79, v0
	v_mov_b32_e32 v88, v0
	v_mov_b32_e32 v89, v0
	v_mov_b32_e32 v90, v0
	v_mov_b32_e32 v91, v0
	v_mov_b32_e32 v92, v0
	v_mov_b32_e32 v93, v0
	v_mov_b32_e32 v94, v0
	v_mov_b32_e32 v95, v0
	v_mov_b32_e32 v104, v0
	v_mov_b32_e32 v105, v0
	v_mov_b32_e32 v106, v0
	v_mov_b32_e32 v107, v0
	v_mov_b32_e32 v108, v0
	v_mov_b32_e32 v109, v0
	v_mov_b32_e32 v110, v0
	v_mov_b32_e32 v111, v0
	v_mov_b32_e32 v120, v0
	v_mov_b32_e32 v121, v0
	v_mov_b32_e32 v122, v0
	v_mov_b32_e32 v123, v0
	v_mov_b32_e32 v124, v0
	v_mov_b32_e32 v125, v0
	v_mov_b32_e32 v126, v0
	v_mov_b32_e32 v127, v0
	v_add_u32_e32 v212, 0x80, v128
	v_add_u32_e32 v213, 0x80, v130
	.p2align	3
	s_nop 0

.LBB0_698:
	s_ashr_i32 s21, s20, 31
	s_lshl_b64 s[22:23], s[20:21], 19
	s_add_u32 s22, s8, s22
	s_addc_u32 s23, s9, s23
	s_and_b64 s[24:25], s[4:5], exec
	s_cselect_b32 s21, s23, s29
	s_cselect_b32 s49, s22, s28
	s_ashr_i32 s19, s18, 31
	s_lshl_b64 s[24:25], s[18:19], 19
	s_add_u32 s24, s36, s24
	s_addc_u32 s25, s37, s25
	s_and_b64 s[30:31], s[4:5], exec
	s_cselect_b32 s19, s25, s27
	s_cselect_b32 s50, s24, s26
	s_add_u32 s51, s26, 0x100
	s_addc_u32 s52, s27, 0
	s_add_u32 s26, s28, 0x40080
	v_mov_b32_e32 v0, 0
	s_addc_u32 s27, s29, 0
	s_mov_b32 s53, -2
	v_mov_b32_e32 v1, v0
	v_mov_b32_e32 v2, v0
	v_mov_b32_e32 v3, v0
	v_mov_b32_e32 v4, v0
	v_mov_b32_e32 v5, v0
	v_mov_b32_e32 v6, v0
	v_mov_b32_e32 v7, v0
	v_mov_b32_e32 v16, v0
	v_mov_b32_e32 v17, v0
	v_mov_b32_e32 v18, v0
	v_mov_b32_e32 v19, v0
	v_mov_b32_e32 v20, v0
	v_mov_b32_e32 v21, v0
	v_mov_b32_e32 v22, v0
	v_mov_b32_e32 v23, v0
	v_mov_b32_e32 v32, v0
	v_mov_b32_e32 v33, v0
	v_mov_b32_e32 v34, v0
	v_mov_b32_e32 v35, v0
	v_mov_b32_e32 v36, v0
	v_mov_b32_e32 v37, v0
	v_mov_b32_e32 v38, v0
	v_mov_b32_e32 v39, v0
	v_mov_b32_e32 v48, v0
	v_mov_b32_e32 v49, v0
	v_mov_b32_e32 v50, v0
	v_mov_b32_e32 v51, v0
	v_mov_b32_e32 v52, v0
	v_mov_b32_e32 v53, v0
	v_mov_b32_e32 v54, v0
	v_mov_b32_e32 v55, v0
	v_mov_b32_e32 v8, v0
	v_mov_b32_e32 v9, v0
	v_mov_b32_e32 v10, v0
	v_mov_b32_e32 v11, v0
	v_mov_b32_e32 v12, v0
	v_mov_b32_e32 v13, v0
	v_mov_b32_e32 v14, v0
	v_mov_b32_e32 v15, v0
	v_mov_b32_e32 v24, v0
	v_mov_b32_e32 v25, v0
	v_mov_b32_e32 v26, v0
	v_mov_b32_e32 v27, v0
	v_mov_b32_e32 v28, v0
	v_mov_b32_e32 v29, v0
	v_mov_b32_e32 v30, v0
	v_mov_b32_e32 v31, v0
	v_mov_b32_e32 v40, v0
	v_mov_b32_e32 v41, v0
	v_mov_b32_e32 v42, v0
	v_mov_b32_e32 v43, v0
	v_mov_b32_e32 v44, v0
	v_mov_b32_e32 v45, v0
	v_mov_b32_e32 v46, v0
	v_mov_b32_e32 v47, v0
	v_mov_b32_e32 v56, v0
	v_mov_b32_e32 v57, v0
	v_mov_b32_e32 v58, v0
	v_mov_b32_e32 v59, v0
	v_mov_b32_e32 v60, v0
	v_mov_b32_e32 v61, v0
	v_mov_b32_e32 v62, v0
	v_mov_b32_e32 v63, v0
	v_mov_b32_e32 v64, v0
	v_mov_b32_e32 v65, v0
	v_mov_b32_e32 v66, v0
	v_mov_b32_e32 v67, v0
	v_mov_b32_e32 v68, v0
	v_mov_b32_e32 v69, v0
	v_mov_b32_e32 v70, v0
	v_mov_b32_e32 v71, v0
	v_mov_b32_e32 v80, v0
	v_mov_b32_e32 v81, v0
	v_mov_b32_e32 v82, v0
	v_mov_b32_e32 v83, v0
	v_mov_b32_e32 v84, v0
	v_mov_b32_e32 v85, v0
	v_mov_b32_e32 v86, v0
	v_mov_b32_e32 v87, v0
	v_mov_b32_e32 v96, v0
	v_mov_b32_e32 v97, v0
	v_mov_b32_e32 v98, v0
	v_mov_b32_e32 v99, v0
	v_mov_b32_e32 v100, v0
	v_mov_b32_e32 v101, v0
	v_mov_b32_e32 v102, v0
	v_mov_b32_e32 v103, v0
	v_mov_b32_e32 v112, v0
	v_mov_b32_e32 v113, v0
	v_mov_b32_e32 v114, v0
	v_mov_b32_e32 v115, v0
	v_mov_b32_e32 v116, v0
	v_mov_b32_e32 v117, v0
	v_mov_b32_e32 v118, v0
	v_mov_b32_e32 v119, v0
	v_mov_b32_e32 v72, v0
	v_mov_b32_e32 v73, v0
	v_mov_b32_e32 v74, v0
	v_mov_b32_e32 v75, v0
	v_mov_b32_e32 v76, v0
	v_mov_b32_e32 v77, v0
	v_mov_b32_e32 v78, v0
	v_mov_b32_e32 v79, v0
	v_mov_b32_e32 v88, v0
	v_mov_b32_e32 v89, v0
	v_mov_b32_e32 v90, v0
	v_mov_b32_e32 v91, v0
	v_mov_b32_e32 v92, v0
	v_mov_b32_e32 v93, v0
	v_mov_b32_e32 v94, v0
	v_mov_b32_e32 v95, v0
	v_mov_b32_e32 v104, v0
	v_mov_b32_e32 v105, v0
	v_mov_b32_e32 v106, v0
	v_mov_b32_e32 v107, v0
	v_mov_b32_e32 v108, v0
	v_mov_b32_e32 v109, v0
	v_mov_b32_e32 v110, v0
	v_mov_b32_e32 v111, v0
	v_mov_b32_e32 v120, v0
	v_mov_b32_e32 v121, v0
	v_mov_b32_e32 v122, v0
	v_mov_b32_e32 v123, v0
	v_mov_b32_e32 v124, v0
	v_mov_b32_e32 v125, v0
	v_mov_b32_e32 v126, v0
	v_mov_b32_e32 v127, v0
	v_add_u32_e32 v204, 0x80, v128
	v_add_u32_e32 v205, 0x80, v130
	v_add_u32_e32 v220, 0x80, v132
	v_add_u32_e32 v221, 0x80, v134
	.p2align	3
	s_nop 0

.LBB0_777:
	s_ashr_i32 s21, s20, 31
	s_lshl_b64 s[22:23], s[20:21], 21
	s_add_u32 s22, s39, s22
	s_addc_u32 s23, s40, s23
	s_and_b64 s[24:25], s[6:7], exec
	s_cselect_b32 s21, s23, s29
	s_cselect_b32 s27, s22, s28
	s_ashr_i32 s19, s18, 31
	s_lshl_b64 s[24:25], s[18:19], 21
	s_add_u32 s24, s41, s24
	s_addc_u32 s25, s42, s25
	s_and_b64 s[34:35], s[6:7], exec
	s_cselect_b32 s19, s25, s31
	s_cselect_b32 s55, s24, s30
	s_add_u32 s56, s30, 0x100
	v_mov_b32_e32 v0, 0
	s_addc_u32 s57, s31, 0
	s_mov_b32 s58, -2
	v_mov_b32_e32 v1, v0
	v_mov_b32_e32 v2, v0
	v_mov_b32_e32 v3, v0
	v_mov_b32_e32 v4, v0
	v_mov_b32_e32 v5, v0
	v_mov_b32_e32 v6, v0
	v_mov_b32_e32 v7, v0
	v_mov_b32_e32 v16, v0
	v_mov_b32_e32 v17, v0
	v_mov_b32_e32 v18, v0
	v_mov_b32_e32 v19, v0
	v_mov_b32_e32 v20, v0
	v_mov_b32_e32 v21, v0
	v_mov_b32_e32 v22, v0
	v_mov_b32_e32 v23, v0
	v_mov_b32_e32 v32, v0
	v_mov_b32_e32 v33, v0
	v_mov_b32_e32 v34, v0
	v_mov_b32_e32 v35, v0
	v_mov_b32_e32 v36, v0
	v_mov_b32_e32 v37, v0
	v_mov_b32_e32 v38, v0
	v_mov_b32_e32 v39, v0
	v_mov_b32_e32 v48, v0
	v_mov_b32_e32 v49, v0
	v_mov_b32_e32 v50, v0
	v_mov_b32_e32 v51, v0
	v_mov_b32_e32 v52, v0
	v_mov_b32_e32 v53, v0
	v_mov_b32_e32 v54, v0
	v_mov_b32_e32 v55, v0
	v_mov_b32_e32 v8, v0
	v_mov_b32_e32 v9, v0
	v_mov_b32_e32 v10, v0
	v_mov_b32_e32 v11, v0
	v_mov_b32_e32 v12, v0
	v_mov_b32_e32 v13, v0
	v_mov_b32_e32 v14, v0
	v_mov_b32_e32 v15, v0
	v_mov_b32_e32 v24, v0
	v_mov_b32_e32 v25, v0
	v_mov_b32_e32 v26, v0
	v_mov_b32_e32 v27, v0
	v_mov_b32_e32 v28, v0
	v_mov_b32_e32 v29, v0
	v_mov_b32_e32 v30, v0
	v_mov_b32_e32 v31, v0
	v_mov_b32_e32 v40, v0
	v_mov_b32_e32 v41, v0
	v_mov_b32_e32 v42, v0
	v_mov_b32_e32 v43, v0
	v_mov_b32_e32 v44, v0
	v_mov_b32_e32 v45, v0
	v_mov_b32_e32 v46, v0
	v_mov_b32_e32 v47, v0
	v_mov_b32_e32 v56, v0
	v_mov_b32_e32 v57, v0
	v_mov_b32_e32 v58, v0
	v_mov_b32_e32 v59, v0
	v_mov_b32_e32 v60, v0
	v_mov_b32_e32 v61, v0
	v_mov_b32_e32 v62, v0
	v_mov_b32_e32 v63, v0
	v_mov_b32_e32 v64, v0
	v_mov_b32_e32 v65, v0
	v_mov_b32_e32 v66, v0
	v_mov_b32_e32 v67, v0
	v_mov_b32_e32 v68, v0
	v_mov_b32_e32 v69, v0
	v_mov_b32_e32 v70, v0
	v_mov_b32_e32 v71, v0
	v_mov_b32_e32 v80, v0
	v_mov_b32_e32 v81, v0
	v_mov_b32_e32 v82, v0
	v_mov_b32_e32 v83, v0
	v_mov_b32_e32 v84, v0
	v_mov_b32_e32 v85, v0
	v_mov_b32_e32 v86, v0
	v_mov_b32_e32 v87, v0
	v_mov_b32_e32 v96, v0
	v_mov_b32_e32 v97, v0
	v_mov_b32_e32 v98, v0
	v_mov_b32_e32 v99, v0
	v_mov_b32_e32 v100, v0
	v_mov_b32_e32 v101, v0
	v_mov_b32_e32 v102, v0
	v_mov_b32_e32 v103, v0
	v_mov_b32_e32 v112, v0
	v_mov_b32_e32 v113, v0
	v_mov_b32_e32 v114, v0
	v_mov_b32_e32 v115, v0
	v_mov_b32_e32 v116, v0
	v_mov_b32_e32 v117, v0
	v_mov_b32_e32 v118, v0
	v_mov_b32_e32 v119, v0
	v_mov_b32_e32 v72, v0
	v_mov_b32_e32 v73, v0
	v_mov_b32_e32 v74, v0
	v_mov_b32_e32 v75, v0
	v_mov_b32_e32 v76, v0
	v_mov_b32_e32 v77, v0
	v_mov_b32_e32 v78, v0
	v_mov_b32_e32 v79, v0
	v_mov_b32_e32 v88, v0
	v_mov_b32_e32 v89, v0
	v_mov_b32_e32 v90, v0
	v_mov_b32_e32 v91, v0
	v_mov_b32_e32 v92, v0
	v_mov_b32_e32 v93, v0
	v_mov_b32_e32 v94, v0
	v_mov_b32_e32 v95, v0
	v_mov_b32_e32 v104, v0
	v_mov_b32_e32 v105, v0
	v_mov_b32_e32 v106, v0
	v_mov_b32_e32 v107, v0
	v_mov_b32_e32 v108, v0
	v_mov_b32_e32 v109, v0
	v_mov_b32_e32 v110, v0
	v_mov_b32_e32 v111, v0
	v_mov_b32_e32 v120, v0
	v_mov_b32_e32 v121, v0
	v_mov_b32_e32 v122, v0
	v_mov_b32_e32 v123, v0
	v_mov_b32_e32 v124, v0
	v_mov_b32_e32 v125, v0
	v_mov_b32_e32 v126, v0
	v_mov_b32_e32 v127, v0
	v_add_u32_e32 v212, 0x80, v128
	v_add_u32_e32 v213, 0x80, v130
	.p2align	3
	s_nop 0

.LBB0_894:
	s_ashr_i32 s29, s28, 31
	s_lshl_b64 s[30:31], s[28:29], 19
	s_add_u32 s30, s8, s30
	s_addc_u32 s31, s9, s31
	s_and_b64 s[34:35], s[6:7], exec
	s_cselect_b32 s3, s31, s39
	s_cselect_b32 s29, s30, s38
	s_ashr_i32 s27, s26, 31
	s_lshl_b64 s[34:35], s[26:27], 19
	s_add_u32 s34, s43, s34
	s_addc_u32 s35, s44, s35
	s_and_b64 s[40:41], s[6:7], exec
	s_cselect_b32 s27, s35, s37
	s_cselect_b32 s58, s34, s36
	s_add_u32 s59, s36, 0x100
	s_addc_u32 s60, s37, 0
	s_add_u32 s36, s38, 0x40080
	v_mov_b32_e32 v0, 0
	s_addc_u32 s37, s39, 0
	s_mov_b32 s61, -2
	v_mov_b32_e32 v1, v0
	v_mov_b32_e32 v2, v0
	v_mov_b32_e32 v3, v0
	v_mov_b32_e32 v4, v0
	v_mov_b32_e32 v5, v0
	v_mov_b32_e32 v6, v0
	v_mov_b32_e32 v7, v0
	v_mov_b32_e32 v16, v0
	v_mov_b32_e32 v17, v0
	v_mov_b32_e32 v18, v0
	v_mov_b32_e32 v19, v0
	v_mov_b32_e32 v20, v0
	v_mov_b32_e32 v21, v0
	v_mov_b32_e32 v22, v0
	v_mov_b32_e32 v23, v0
	v_mov_b32_e32 v32, v0
	v_mov_b32_e32 v33, v0
	v_mov_b32_e32 v34, v0
	v_mov_b32_e32 v35, v0
	v_mov_b32_e32 v36, v0
	v_mov_b32_e32 v37, v0
	v_mov_b32_e32 v38, v0
	v_mov_b32_e32 v39, v0
	v_mov_b32_e32 v48, v0
	v_mov_b32_e32 v49, v0
	v_mov_b32_e32 v50, v0
	v_mov_b32_e32 v51, v0
	v_mov_b32_e32 v52, v0
	v_mov_b32_e32 v53, v0
	v_mov_b32_e32 v54, v0
	v_mov_b32_e32 v55, v0
	v_mov_b32_e32 v8, v0
	v_mov_b32_e32 v9, v0
	v_mov_b32_e32 v10, v0
	v_mov_b32_e32 v11, v0
	v_mov_b32_e32 v12, v0
	v_mov_b32_e32 v13, v0
	v_mov_b32_e32 v14, v0
	v_mov_b32_e32 v15, v0
	v_mov_b32_e32 v24, v0
	v_mov_b32_e32 v25, v0
	v_mov_b32_e32 v26, v0
	v_mov_b32_e32 v27, v0
	v_mov_b32_e32 v28, v0
	v_mov_b32_e32 v29, v0
	v_mov_b32_e32 v30, v0
	v_mov_b32_e32 v31, v0
	v_mov_b32_e32 v40, v0
	v_mov_b32_e32 v41, v0
	v_mov_b32_e32 v42, v0
	v_mov_b32_e32 v43, v0
	v_mov_b32_e32 v44, v0
	v_mov_b32_e32 v45, v0
	v_mov_b32_e32 v46, v0
	v_mov_b32_e32 v47, v0
	v_mov_b32_e32 v56, v0
	v_mov_b32_e32 v57, v0
	v_mov_b32_e32 v58, v0
	v_mov_b32_e32 v59, v0
	v_mov_b32_e32 v60, v0
	v_mov_b32_e32 v61, v0
	v_mov_b32_e32 v62, v0
	v_mov_b32_e32 v63, v0
	v_mov_b32_e32 v64, v0
	v_mov_b32_e32 v65, v0
	v_mov_b32_e32 v66, v0
	v_mov_b32_e32 v67, v0
	v_mov_b32_e32 v68, v0
	v_mov_b32_e32 v69, v0
	v_mov_b32_e32 v70, v0
	v_mov_b32_e32 v71, v0
	v_mov_b32_e32 v80, v0
	v_mov_b32_e32 v81, v0
	v_mov_b32_e32 v82, v0
	v_mov_b32_e32 v83, v0
	v_mov_b32_e32 v84, v0
	v_mov_b32_e32 v85, v0
	v_mov_b32_e32 v86, v0
	v_mov_b32_e32 v87, v0
	v_mov_b32_e32 v96, v0
	v_mov_b32_e32 v97, v0
	v_mov_b32_e32 v98, v0
	v_mov_b32_e32 v99, v0
	v_mov_b32_e32 v100, v0
	v_mov_b32_e32 v101, v0
	v_mov_b32_e32 v102, v0
	v_mov_b32_e32 v103, v0
	v_mov_b32_e32 v112, v0
	v_mov_b32_e32 v113, v0
	v_mov_b32_e32 v114, v0
	v_mov_b32_e32 v115, v0
	v_mov_b32_e32 v116, v0
	v_mov_b32_e32 v117, v0
	v_mov_b32_e32 v118, v0
	v_mov_b32_e32 v119, v0
	v_mov_b32_e32 v72, v0
	v_mov_b32_e32 v73, v0
	v_mov_b32_e32 v74, v0
	v_mov_b32_e32 v75, v0
	v_mov_b32_e32 v76, v0
	v_mov_b32_e32 v77, v0
	v_mov_b32_e32 v78, v0
	v_mov_b32_e32 v79, v0
	v_mov_b32_e32 v88, v0
	v_mov_b32_e32 v89, v0
	v_mov_b32_e32 v90, v0
	v_mov_b32_e32 v91, v0
	v_mov_b32_e32 v92, v0
	v_mov_b32_e32 v93, v0
	v_mov_b32_e32 v94, v0
	v_mov_b32_e32 v95, v0
	v_mov_b32_e32 v104, v0
	v_mov_b32_e32 v105, v0
	v_mov_b32_e32 v106, v0
	v_mov_b32_e32 v107, v0
	v_mov_b32_e32 v108, v0
	v_mov_b32_e32 v109, v0
	v_mov_b32_e32 v110, v0
	v_mov_b32_e32 v111, v0
	v_mov_b32_e32 v120, v0
	v_mov_b32_e32 v121, v0
	v_mov_b32_e32 v122, v0
	v_mov_b32_e32 v123, v0
	v_mov_b32_e32 v124, v0
	v_mov_b32_e32 v125, v0
	v_mov_b32_e32 v126, v0
	v_mov_b32_e32 v127, v0
	v_add_u32_e32 v148, 0x80, v128
	v_add_u32_e32 v149, 0x80, v130
	.p2align	3
	s_nop 0

.LBB0_987:
	s_ashr_i32 s19, s18, 31
	s_lshl_b64 s[6:7], s[18:19], 19
	s_add_u32 s20, s34, s6
	s_addc_u32 s21, s35, s7
	s_and_b64 s[6:7], s[4:5], exec
	s_cselect_b32 s19, s21, s29
	s_cselect_b32 s49, s20, s28
	s_ashr_i32 s17, s16, 31
	s_lshl_b64 s[6:7], s[16:17], 19
	s_add_u32 s22, s36, s6
	s_addc_u32 s23, s37, s7
	s_and_b64 s[6:7], s[4:5], exec
	s_cselect_b32 s17, s23, s27
	s_cselect_b32 s50, s22, s26
	s_add_u32 s51, s26, 0x100
	s_addc_u32 s52, s27, 0
	s_add_u32 s6, s28, 0x40080
	v_mov_b32_e32 v0, 0
	s_addc_u32 s7, s29, 0
	s_mov_b32 s53, -2
	v_mov_b32_e32 v1, v0
	v_mov_b32_e32 v2, v0
	v_mov_b32_e32 v3, v0
	v_mov_b32_e32 v4, v0
	v_mov_b32_e32 v5, v0
	v_mov_b32_e32 v6, v0
	v_mov_b32_e32 v7, v0
	v_mov_b32_e32 v16, v0
	v_mov_b32_e32 v17, v0
	v_mov_b32_e32 v18, v0
	v_mov_b32_e32 v19, v0
	v_mov_b32_e32 v20, v0
	v_mov_b32_e32 v21, v0
	v_mov_b32_e32 v22, v0
	v_mov_b32_e32 v23, v0
	v_mov_b32_e32 v32, v0
	v_mov_b32_e32 v33, v0
	v_mov_b32_e32 v34, v0
	v_mov_b32_e32 v35, v0
	v_mov_b32_e32 v36, v0
	v_mov_b32_e32 v37, v0
	v_mov_b32_e32 v38, v0
	v_mov_b32_e32 v39, v0
	v_mov_b32_e32 v48, v0
	v_mov_b32_e32 v49, v0
	v_mov_b32_e32 v50, v0
	v_mov_b32_e32 v51, v0
	v_mov_b32_e32 v52, v0
	v_mov_b32_e32 v53, v0
	v_mov_b32_e32 v54, v0
	v_mov_b32_e32 v55, v0
	v_mov_b32_e32 v8, v0
	v_mov_b32_e32 v9, v0
	v_mov_b32_e32 v10, v0
	v_mov_b32_e32 v11, v0
	v_mov_b32_e32 v12, v0
	v_mov_b32_e32 v13, v0
	v_mov_b32_e32 v14, v0
	v_mov_b32_e32 v15, v0
	v_mov_b32_e32 v24, v0
	v_mov_b32_e32 v25, v0
	v_mov_b32_e32 v26, v0
	v_mov_b32_e32 v27, v0
	v_mov_b32_e32 v28, v0
	v_mov_b32_e32 v29, v0
	v_mov_b32_e32 v30, v0
	v_mov_b32_e32 v31, v0
	v_mov_b32_e32 v40, v0
	v_mov_b32_e32 v41, v0
	v_mov_b32_e32 v42, v0
	v_mov_b32_e32 v43, v0
	v_mov_b32_e32 v44, v0
	v_mov_b32_e32 v45, v0
	v_mov_b32_e32 v46, v0
	v_mov_b32_e32 v47, v0
	v_mov_b32_e32 v56, v0
	v_mov_b32_e32 v57, v0
	v_mov_b32_e32 v58, v0
	v_mov_b32_e32 v59, v0
	v_mov_b32_e32 v60, v0
	v_mov_b32_e32 v61, v0
	v_mov_b32_e32 v62, v0
	v_mov_b32_e32 v63, v0
	v_mov_b32_e32 v64, v0
	v_mov_b32_e32 v65, v0
	v_mov_b32_e32 v66, v0
	v_mov_b32_e32 v67, v0
	v_mov_b32_e32 v68, v0
	v_mov_b32_e32 v69, v0
	v_mov_b32_e32 v70, v0
	v_mov_b32_e32 v71, v0
	v_mov_b32_e32 v80, v0
	v_mov_b32_e32 v81, v0
	v_mov_b32_e32 v82, v0
	v_mov_b32_e32 v83, v0
	v_mov_b32_e32 v84, v0
	v_mov_b32_e32 v85, v0
	v_mov_b32_e32 v86, v0
	v_mov_b32_e32 v87, v0
	v_mov_b32_e32 v96, v0
	v_mov_b32_e32 v97, v0
	v_mov_b32_e32 v98, v0
	v_mov_b32_e32 v99, v0
	v_mov_b32_e32 v100, v0
	v_mov_b32_e32 v101, v0
	v_mov_b32_e32 v102, v0
	v_mov_b32_e32 v103, v0
	v_mov_b32_e32 v112, v0
	v_mov_b32_e32 v113, v0
	v_mov_b32_e32 v114, v0
	v_mov_b32_e32 v115, v0
	v_mov_b32_e32 v116, v0
	v_mov_b32_e32 v117, v0
	v_mov_b32_e32 v118, v0
	v_mov_b32_e32 v119, v0
	v_mov_b32_e32 v72, v0
	v_mov_b32_e32 v73, v0
	v_mov_b32_e32 v74, v0
	v_mov_b32_e32 v75, v0
	v_mov_b32_e32 v76, v0
	v_mov_b32_e32 v77, v0
	v_mov_b32_e32 v78, v0
	v_mov_b32_e32 v79, v0
	v_mov_b32_e32 v88, v0
	v_mov_b32_e32 v89, v0
	v_mov_b32_e32 v90, v0
	v_mov_b32_e32 v91, v0
	v_mov_b32_e32 v92, v0
	v_mov_b32_e32 v93, v0
	v_mov_b32_e32 v94, v0
	v_mov_b32_e32 v95, v0
	v_mov_b32_e32 v104, v0
	v_mov_b32_e32 v105, v0
	v_mov_b32_e32 v106, v0
	v_mov_b32_e32 v107, v0
	v_mov_b32_e32 v108, v0
	v_mov_b32_e32 v109, v0
	v_mov_b32_e32 v110, v0
	v_mov_b32_e32 v111, v0
	v_mov_b32_e32 v120, v0
	v_mov_b32_e32 v121, v0
	v_mov_b32_e32 v122, v0
	v_mov_b32_e32 v123, v0
	v_mov_b32_e32 v124, v0
	v_mov_b32_e32 v125, v0
	v_mov_b32_e32 v126, v0
	v_mov_b32_e32 v127, v0
	v_add_u32_e32 v204, 0x80, v128
	v_add_u32_e32 v205, 0x80, v130
	v_add_u32_e32 v220, 0x80, v132
	v_add_u32_e32 v221, 0x80, v134
	.p2align	3
	s_nop 0

.LBB0_1192:
	s_ashr_i32 s17, s16, 31
	s_lshl_b64 s[18:19], s[16:17], 18
	s_add_u32 s18, s6, s18
	s_addc_u32 s19, s7, s19
	s_and_b64 s[20:21], s[4:5], exec
	s_cselect_b32 s17, s19, s27
	s_cselect_b32 s46, s18, s26
	s_ashr_i32 s15, s14, 31
	s_lshl_b64 s[20:21], s[14:15], 18
	s_add_u32 s20, s34, s20
	s_addc_u32 s21, s35, s21
	s_and_b64 s[28:29], s[4:5], exec
	s_cselect_b32 s15, s21, s25
	s_cselect_b32 s47, s20, s24
	s_add_u32 s48, s24, 0x100
	s_addc_u32 s49, s25, 0
	s_add_u32 s24, s26, 0x20080
	v_mov_b32_e32 v0, 0
	s_addc_u32 s25, s27, 0
	s_mov_b32 s50, -2
	v_mov_b32_e32 v1, v0
	v_mov_b32_e32 v2, v0
	v_mov_b32_e32 v3, v0
	v_mov_b32_e32 v4, v0
	v_mov_b32_e32 v5, v0
	v_mov_b32_e32 v6, v0
	v_mov_b32_e32 v7, v0
	v_mov_b32_e32 v16, v0
	v_mov_b32_e32 v17, v0
	v_mov_b32_e32 v18, v0
	v_mov_b32_e32 v19, v0
	v_mov_b32_e32 v20, v0
	v_mov_b32_e32 v21, v0
	v_mov_b32_e32 v22, v0
	v_mov_b32_e32 v23, v0
	v_mov_b32_e32 v32, v0
	v_mov_b32_e32 v33, v0
	v_mov_b32_e32 v34, v0
	v_mov_b32_e32 v35, v0
	v_mov_b32_e32 v36, v0
	v_mov_b32_e32 v37, v0
	v_mov_b32_e32 v38, v0
	v_mov_b32_e32 v39, v0
	v_mov_b32_e32 v48, v0
	v_mov_b32_e32 v49, v0
	v_mov_b32_e32 v50, v0
	v_mov_b32_e32 v51, v0
	v_mov_b32_e32 v52, v0
	v_mov_b32_e32 v53, v0
	v_mov_b32_e32 v54, v0
	v_mov_b32_e32 v55, v0
	v_mov_b32_e32 v8, v0
	v_mov_b32_e32 v9, v0
	v_mov_b32_e32 v10, v0
	v_mov_b32_e32 v11, v0
	v_mov_b32_e32 v12, v0
	v_mov_b32_e32 v13, v0
	v_mov_b32_e32 v14, v0
	v_mov_b32_e32 v15, v0
	v_mov_b32_e32 v24, v0
	v_mov_b32_e32 v25, v0
	v_mov_b32_e32 v26, v0
	v_mov_b32_e32 v27, v0
	v_mov_b32_e32 v28, v0
	v_mov_b32_e32 v29, v0
	v_mov_b32_e32 v30, v0
	v_mov_b32_e32 v31, v0
	v_mov_b32_e32 v40, v0
	v_mov_b32_e32 v41, v0
	v_mov_b32_e32 v42, v0
	v_mov_b32_e32 v43, v0
	v_mov_b32_e32 v44, v0
	v_mov_b32_e32 v45, v0
	v_mov_b32_e32 v46, v0
	v_mov_b32_e32 v47, v0
	v_mov_b32_e32 v56, v0
	v_mov_b32_e32 v57, v0
	v_mov_b32_e32 v58, v0
	v_mov_b32_e32 v59, v0
	v_mov_b32_e32 v60, v0
	v_mov_b32_e32 v61, v0
	v_mov_b32_e32 v62, v0
	v_mov_b32_e32 v63, v0
	v_mov_b32_e32 v64, v0
	v_mov_b32_e32 v65, v0
	v_mov_b32_e32 v66, v0
	v_mov_b32_e32 v67, v0
	v_mov_b32_e32 v68, v0
	v_mov_b32_e32 v69, v0
	v_mov_b32_e32 v70, v0
	v_mov_b32_e32 v71, v0
	v_mov_b32_e32 v80, v0
	v_mov_b32_e32 v81, v0
	v_mov_b32_e32 v82, v0
	v_mov_b32_e32 v83, v0
	v_mov_b32_e32 v84, v0
	v_mov_b32_e32 v85, v0
	v_mov_b32_e32 v86, v0
	v_mov_b32_e32 v87, v0
	v_mov_b32_e32 v96, v0
	v_mov_b32_e32 v97, v0
	v_mov_b32_e32 v98, v0
	v_mov_b32_e32 v99, v0
	v_mov_b32_e32 v100, v0
	v_mov_b32_e32 v101, v0
	v_mov_b32_e32 v102, v0
	v_mov_b32_e32 v103, v0
	v_mov_b32_e32 v112, v0
	v_mov_b32_e32 v113, v0
	v_mov_b32_e32 v114, v0
	v_mov_b32_e32 v115, v0
	v_mov_b32_e32 v116, v0
	v_mov_b32_e32 v117, v0
	v_mov_b32_e32 v118, v0
	v_mov_b32_e32 v119, v0
	v_mov_b32_e32 v72, v0
	v_mov_b32_e32 v73, v0
	v_mov_b32_e32 v74, v0
	v_mov_b32_e32 v75, v0
	v_mov_b32_e32 v76, v0
	v_mov_b32_e32 v77, v0
	v_mov_b32_e32 v78, v0
	v_mov_b32_e32 v79, v0
	v_mov_b32_e32 v88, v0
	v_mov_b32_e32 v89, v0
	v_mov_b32_e32 v90, v0
	v_mov_b32_e32 v91, v0
	v_mov_b32_e32 v92, v0
	v_mov_b32_e32 v93, v0
	v_mov_b32_e32 v94, v0
	v_mov_b32_e32 v95, v0
	v_mov_b32_e32 v104, v0
	v_mov_b32_e32 v105, v0
	v_mov_b32_e32 v106, v0
	v_mov_b32_e32 v107, v0
	v_mov_b32_e32 v108, v0
	v_mov_b32_e32 v109, v0
	v_mov_b32_e32 v110, v0
	v_mov_b32_e32 v111, v0
	v_mov_b32_e32 v120, v0
	v_mov_b32_e32 v121, v0
	v_mov_b32_e32 v122, v0
	v_mov_b32_e32 v123, v0
	v_mov_b32_e32 v124, v0
	v_mov_b32_e32 v125, v0
	v_mov_b32_e32 v126, v0
	v_mov_b32_e32 v127, v0
	v_add_u32_e32 v216, 0x80, v128
	v_add_u32_e32 v217, 0x80, v130
	v_add_u32_e32 v218, 0x80, v132
	v_add_u32_e32 v219, 0x80, v134
	.p2align	3
	s_nop 0

.LBB0_1364:
	s_ashr_i32 s19, s18, 31
	s_lshl_b64 s[20:21], s[18:19], 19
	s_add_u32 s20, s34, s20
	s_addc_u32 s21, s35, s21
	s_and_b64 s[22:23], s[4:5], exec
	s_cselect_b32 s19, s21, s27
	s_cselect_b32 s49, s20, s26
	s_ashr_i32 s17, s16, 31
	s_lshl_b64 s[22:23], s[16:17], 19
	s_add_u32 s22, s36, s22
	s_addc_u32 s23, s37, s23
	s_and_b64 s[28:29], s[4:5], exec
	s_cselect_b32 s17, s23, s25
	s_cselect_b32 s50, s22, s24
	s_add_u32 s51, s24, 0x100
	s_addc_u32 s52, s25, 0
	s_add_u32 s24, s26, 0x40080
	v_mov_b32_e32 v0, 0
	s_addc_u32 s25, s27, 0
	s_mov_b32 s53, -2
	v_mov_b32_e32 v1, v0
	v_mov_b32_e32 v2, v0
	v_mov_b32_e32 v3, v0
	v_mov_b32_e32 v4, v0
	v_mov_b32_e32 v5, v0
	v_mov_b32_e32 v6, v0
	v_mov_b32_e32 v7, v0
	v_mov_b32_e32 v16, v0
	v_mov_b32_e32 v17, v0
	v_mov_b32_e32 v18, v0
	v_mov_b32_e32 v19, v0
	v_mov_b32_e32 v20, v0
	v_mov_b32_e32 v21, v0
	v_mov_b32_e32 v22, v0
	v_mov_b32_e32 v23, v0
	v_mov_b32_e32 v32, v0
	v_mov_b32_e32 v33, v0
	v_mov_b32_e32 v34, v0
	v_mov_b32_e32 v35, v0
	v_mov_b32_e32 v36, v0
	v_mov_b32_e32 v37, v0
	v_mov_b32_e32 v38, v0
	v_mov_b32_e32 v39, v0
	v_mov_b32_e32 v48, v0
	v_mov_b32_e32 v49, v0
	v_mov_b32_e32 v50, v0
	v_mov_b32_e32 v51, v0
	v_mov_b32_e32 v52, v0
	v_mov_b32_e32 v53, v0
	v_mov_b32_e32 v54, v0
	v_mov_b32_e32 v55, v0
	v_mov_b32_e32 v8, v0
	v_mov_b32_e32 v9, v0
	v_mov_b32_e32 v10, v0
	v_mov_b32_e32 v11, v0
	v_mov_b32_e32 v12, v0
	v_mov_b32_e32 v13, v0
	v_mov_b32_e32 v14, v0
	v_mov_b32_e32 v15, v0
	v_mov_b32_e32 v24, v0
	v_mov_b32_e32 v25, v0
	v_mov_b32_e32 v26, v0
	v_mov_b32_e32 v27, v0
	v_mov_b32_e32 v28, v0
	v_mov_b32_e32 v29, v0
	v_mov_b32_e32 v30, v0
	v_mov_b32_e32 v31, v0
	v_mov_b32_e32 v40, v0
	v_mov_b32_e32 v41, v0
	v_mov_b32_e32 v42, v0
	v_mov_b32_e32 v43, v0
	v_mov_b32_e32 v44, v0
	v_mov_b32_e32 v45, v0
	v_mov_b32_e32 v46, v0
	v_mov_b32_e32 v47, v0
	v_mov_b32_e32 v56, v0
	v_mov_b32_e32 v57, v0
	v_mov_b32_e32 v58, v0
	v_mov_b32_e32 v59, v0
	v_mov_b32_e32 v60, v0
	v_mov_b32_e32 v61, v0
	v_mov_b32_e32 v62, v0
	v_mov_b32_e32 v63, v0
	v_mov_b32_e32 v64, v0
	v_mov_b32_e32 v65, v0
	v_mov_b32_e32 v66, v0
	v_mov_b32_e32 v67, v0
	v_mov_b32_e32 v68, v0
	v_mov_b32_e32 v69, v0
	v_mov_b32_e32 v70, v0
	v_mov_b32_e32 v71, v0
	v_mov_b32_e32 v80, v0
	v_mov_b32_e32 v81, v0
	v_mov_b32_e32 v82, v0
	v_mov_b32_e32 v83, v0
	v_mov_b32_e32 v84, v0
	v_mov_b32_e32 v85, v0
	v_mov_b32_e32 v86, v0
	v_mov_b32_e32 v87, v0
	v_mov_b32_e32 v96, v0
	v_mov_b32_e32 v97, v0
	v_mov_b32_e32 v98, v0
	v_mov_b32_e32 v99, v0
	v_mov_b32_e32 v100, v0
	v_mov_b32_e32 v101, v0
	v_mov_b32_e32 v102, v0
	v_mov_b32_e32 v103, v0
	v_mov_b32_e32 v112, v0
	v_mov_b32_e32 v113, v0
	v_mov_b32_e32 v114, v0
	v_mov_b32_e32 v115, v0
	v_mov_b32_e32 v116, v0
	v_mov_b32_e32 v117, v0
	v_mov_b32_e32 v118, v0
	v_mov_b32_e32 v119, v0
	v_mov_b32_e32 v72, v0
	v_mov_b32_e32 v73, v0
	v_mov_b32_e32 v74, v0
	v_mov_b32_e32 v75, v0
	v_mov_b32_e32 v76, v0
	v_mov_b32_e32 v77, v0
	v_mov_b32_e32 v78, v0
	v_mov_b32_e32 v79, v0
	v_mov_b32_e32 v88, v0
	v_mov_b32_e32 v89, v0
	v_mov_b32_e32 v90, v0
	v_mov_b32_e32 v91, v0
	v_mov_b32_e32 v92, v0
	v_mov_b32_e32 v93, v0
	v_mov_b32_e32 v94, v0
	v_mov_b32_e32 v95, v0
	v_mov_b32_e32 v104, v0
	v_mov_b32_e32 v105, v0
	v_mov_b32_e32 v106, v0
	v_mov_b32_e32 v107, v0
	v_mov_b32_e32 v108, v0
	v_mov_b32_e32 v109, v0
	v_mov_b32_e32 v110, v0
	v_mov_b32_e32 v111, v0
	v_mov_b32_e32 v120, v0
	v_mov_b32_e32 v121, v0
	v_mov_b32_e32 v122, v0
	v_mov_b32_e32 v123, v0
	v_mov_b32_e32 v124, v0
	v_mov_b32_e32 v125, v0
	v_mov_b32_e32 v126, v0
	v_mov_b32_e32 v127, v0
	v_add_u32_e32 v204, 0x80, v128
	v_add_u32_e32 v205, 0x80, v130
	v_add_u32_e32 v220, 0x80, v132
	v_add_u32_e32 v221, 0x80, v134
	.p2align	3
	s_nop 0

.LBB0_1560:
	s_ashr_i32 s29, s28, 31
	s_lshl_b64 s[30:31], s[28:29], 19
	s_add_u32 s30, s12, s30
	s_addc_u32 s31, s13, s31
	s_and_b64 s[34:35], s[6:7], exec
	s_cselect_b32 s3, s31, s39
	s_cselect_b32 s29, s30, s38
	s_ashr_i32 s27, s26, 31
	s_lshl_b64 s[34:35], s[26:27], 19
	s_add_u32 s34, s43, s34
	s_addc_u32 s35, s44, s35
	s_and_b64 s[40:41], s[6:7], exec
	s_cselect_b32 s27, s35, s37
	s_cselect_b32 s58, s34, s36
	s_add_u32 s59, s36, 0x100
	s_addc_u32 s60, s37, 0
	s_add_u32 s36, s38, 0x40080
	v_mov_b32_e32 v0, 0
	s_addc_u32 s37, s39, 0
	s_mov_b32 s61, -2
	v_mov_b32_e32 v1, v0
	v_mov_b32_e32 v2, v0
	v_mov_b32_e32 v3, v0
	v_mov_b32_e32 v4, v0
	v_mov_b32_e32 v5, v0
	v_mov_b32_e32 v6, v0
	v_mov_b32_e32 v7, v0
	v_mov_b32_e32 v16, v0
	v_mov_b32_e32 v17, v0
	v_mov_b32_e32 v18, v0
	v_mov_b32_e32 v19, v0
	v_mov_b32_e32 v20, v0
	v_mov_b32_e32 v21, v0
	v_mov_b32_e32 v22, v0
	v_mov_b32_e32 v23, v0
	v_mov_b32_e32 v32, v0
	v_mov_b32_e32 v33, v0
	v_mov_b32_e32 v34, v0
	v_mov_b32_e32 v35, v0
	v_mov_b32_e32 v36, v0
	v_mov_b32_e32 v37, v0
	v_mov_b32_e32 v38, v0
	v_mov_b32_e32 v39, v0
	v_mov_b32_e32 v48, v0
	v_mov_b32_e32 v49, v0
	v_mov_b32_e32 v50, v0
	v_mov_b32_e32 v51, v0
	v_mov_b32_e32 v52, v0
	v_mov_b32_e32 v53, v0
	v_mov_b32_e32 v54, v0
	v_mov_b32_e32 v55, v0
	v_mov_b32_e32 v8, v0
	v_mov_b32_e32 v9, v0
	v_mov_b32_e32 v10, v0
	v_mov_b32_e32 v11, v0
	v_mov_b32_e32 v12, v0
	v_mov_b32_e32 v13, v0
	v_mov_b32_e32 v14, v0
	v_mov_b32_e32 v15, v0
	v_mov_b32_e32 v24, v0
	v_mov_b32_e32 v25, v0
	v_mov_b32_e32 v26, v0
	v_mov_b32_e32 v27, v0
	v_mov_b32_e32 v28, v0
	v_mov_b32_e32 v29, v0
	v_mov_b32_e32 v30, v0
	v_mov_b32_e32 v31, v0
	v_mov_b32_e32 v40, v0
	v_mov_b32_e32 v41, v0
	v_mov_b32_e32 v42, v0
	v_mov_b32_e32 v43, v0
	v_mov_b32_e32 v44, v0
	v_mov_b32_e32 v45, v0
	v_mov_b32_e32 v46, v0
	v_mov_b32_e32 v47, v0
	v_mov_b32_e32 v56, v0
	v_mov_b32_e32 v57, v0
	v_mov_b32_e32 v58, v0
	v_mov_b32_e32 v59, v0
	v_mov_b32_e32 v60, v0
	v_mov_b32_e32 v61, v0
	v_mov_b32_e32 v62, v0
	v_mov_b32_e32 v63, v0
	v_mov_b32_e32 v64, v0
	v_mov_b32_e32 v65, v0
	v_mov_b32_e32 v66, v0
	v_mov_b32_e32 v67, v0
	v_mov_b32_e32 v68, v0
	v_mov_b32_e32 v69, v0
	v_mov_b32_e32 v70, v0
	v_mov_b32_e32 v71, v0
	v_mov_b32_e32 v80, v0
	v_mov_b32_e32 v81, v0
	v_mov_b32_e32 v82, v0
	v_mov_b32_e32 v83, v0
	v_mov_b32_e32 v84, v0
	v_mov_b32_e32 v85, v0
	v_mov_b32_e32 v86, v0
	v_mov_b32_e32 v87, v0
	v_mov_b32_e32 v96, v0
	v_mov_b32_e32 v97, v0
	v_mov_b32_e32 v98, v0
	v_mov_b32_e32 v99, v0
	v_mov_b32_e32 v100, v0
	v_mov_b32_e32 v101, v0
	v_mov_b32_e32 v102, v0
	v_mov_b32_e32 v103, v0
	v_mov_b32_e32 v112, v0
	v_mov_b32_e32 v113, v0
	v_mov_b32_e32 v114, v0
	v_mov_b32_e32 v115, v0
	v_mov_b32_e32 v116, v0
	v_mov_b32_e32 v117, v0
	v_mov_b32_e32 v118, v0
	v_mov_b32_e32 v119, v0
	v_mov_b32_e32 v72, v0
	v_mov_b32_e32 v73, v0
	v_mov_b32_e32 v74, v0
	v_mov_b32_e32 v75, v0
	v_mov_b32_e32 v76, v0
	v_mov_b32_e32 v77, v0
	v_mov_b32_e32 v78, v0
	v_mov_b32_e32 v79, v0
	v_mov_b32_e32 v88, v0
	v_mov_b32_e32 v89, v0
	v_mov_b32_e32 v90, v0
	v_mov_b32_e32 v91, v0
	v_mov_b32_e32 v92, v0
	v_mov_b32_e32 v93, v0
	v_mov_b32_e32 v94, v0
	v_mov_b32_e32 v95, v0
	v_mov_b32_e32 v104, v0
	v_mov_b32_e32 v105, v0
	v_mov_b32_e32 v106, v0
	v_mov_b32_e32 v107, v0
	v_mov_b32_e32 v108, v0
	v_mov_b32_e32 v109, v0
	v_mov_b32_e32 v110, v0
	v_mov_b32_e32 v111, v0
	v_mov_b32_e32 v120, v0
	v_mov_b32_e32 v121, v0
	v_mov_b32_e32 v122, v0
	v_mov_b32_e32 v123, v0
	v_mov_b32_e32 v124, v0
	v_mov_b32_e32 v125, v0
	v_mov_b32_e32 v126, v0
	v_mov_b32_e32 v127, v0
	v_add_u32_e32 v204, 0x80, v128
	v_add_u32_e32 v205, 0x80, v130
	.p2align	3
	s_nop 0

.LBB0_1645:
	s_ashr_i32 s19, s18, 31
	s_lshl_b64 s[20:21], s[18:19], 19
	s_add_u32 s20, s8, s20
	s_addc_u32 s21, s9, s21
	s_and_b64 s[22:23], s[4:5], exec
	s_cselect_b32 s19, s21, s27
	s_cselect_b32 s50, s20, s26
	s_ashr_i32 s17, s16, 31
	s_lshl_b64 s[22:23], s[16:17], 19
	s_add_u32 s22, s31, s22
	s_addc_u32 s23, s34, s23
	s_and_b64 s[28:29], s[4:5], exec
	s_cselect_b32 s17, s23, s25
	s_cselect_b32 s51, s22, s24
	s_add_u32 s52, s24, 0x100
	s_addc_u32 s53, s25, 0
	s_add_u32 s24, s26, 0x40080
	v_mov_b32_e32 v0, 0
	s_addc_u32 s25, s27, 0
	s_mov_b32 s54, -2
	v_mov_b32_e32 v1, v0
	v_mov_b32_e32 v2, v0
	v_mov_b32_e32 v3, v0
	v_mov_b32_e32 v4, v0
	v_mov_b32_e32 v5, v0
	v_mov_b32_e32 v6, v0
	v_mov_b32_e32 v7, v0
	v_mov_b32_e32 v16, v0
	v_mov_b32_e32 v17, v0
	v_mov_b32_e32 v18, v0
	v_mov_b32_e32 v19, v0
	v_mov_b32_e32 v20, v0
	v_mov_b32_e32 v21, v0
	v_mov_b32_e32 v22, v0
	v_mov_b32_e32 v23, v0
	v_mov_b32_e32 v32, v0
	v_mov_b32_e32 v33, v0
	v_mov_b32_e32 v34, v0
	v_mov_b32_e32 v35, v0
	v_mov_b32_e32 v36, v0
	v_mov_b32_e32 v37, v0
	v_mov_b32_e32 v38, v0
	v_mov_b32_e32 v39, v0
	v_mov_b32_e32 v48, v0
	v_mov_b32_e32 v49, v0
	v_mov_b32_e32 v50, v0
	v_mov_b32_e32 v51, v0
	v_mov_b32_e32 v52, v0
	v_mov_b32_e32 v53, v0
	v_mov_b32_e32 v54, v0
	v_mov_b32_e32 v55, v0
	v_mov_b32_e32 v8, v0
	v_mov_b32_e32 v9, v0
	v_mov_b32_e32 v10, v0
	v_mov_b32_e32 v11, v0
	v_mov_b32_e32 v12, v0
	v_mov_b32_e32 v13, v0
	v_mov_b32_e32 v14, v0
	v_mov_b32_e32 v15, v0
	v_mov_b32_e32 v24, v0
	v_mov_b32_e32 v25, v0
	v_mov_b32_e32 v26, v0
	v_mov_b32_e32 v27, v0
	v_mov_b32_e32 v28, v0
	v_mov_b32_e32 v29, v0
	v_mov_b32_e32 v30, v0
	v_mov_b32_e32 v31, v0
	v_mov_b32_e32 v40, v0
	v_mov_b32_e32 v41, v0
	v_mov_b32_e32 v42, v0
	v_mov_b32_e32 v43, v0
	v_mov_b32_e32 v44, v0
	v_mov_b32_e32 v45, v0
	v_mov_b32_e32 v46, v0
	v_mov_b32_e32 v47, v0
	v_mov_b32_e32 v56, v0
	v_mov_b32_e32 v57, v0
	v_mov_b32_e32 v58, v0
	v_mov_b32_e32 v59, v0
	v_mov_b32_e32 v60, v0
	v_mov_b32_e32 v61, v0
	v_mov_b32_e32 v62, v0
	v_mov_b32_e32 v63, v0
	v_mov_b32_e32 v64, v0
	v_mov_b32_e32 v65, v0
	v_mov_b32_e32 v66, v0
	v_mov_b32_e32 v67, v0
	v_mov_b32_e32 v68, v0
	v_mov_b32_e32 v69, v0
	v_mov_b32_e32 v70, v0
	v_mov_b32_e32 v71, v0
	v_mov_b32_e32 v80, v0
	v_mov_b32_e32 v81, v0
	v_mov_b32_e32 v82, v0
	v_mov_b32_e32 v83, v0
	v_mov_b32_e32 v84, v0
	v_mov_b32_e32 v85, v0
	v_mov_b32_e32 v86, v0
	v_mov_b32_e32 v87, v0
	v_mov_b32_e32 v96, v0
	v_mov_b32_e32 v97, v0
	v_mov_b32_e32 v98, v0
	v_mov_b32_e32 v99, v0
	v_mov_b32_e32 v100, v0
	v_mov_b32_e32 v101, v0
	v_mov_b32_e32 v102, v0
	v_mov_b32_e32 v103, v0
	v_mov_b32_e32 v112, v0
	v_mov_b32_e32 v113, v0
	v_mov_b32_e32 v114, v0
	v_mov_b32_e32 v115, v0
	v_mov_b32_e32 v116, v0
	v_mov_b32_e32 v117, v0
	v_mov_b32_e32 v118, v0
	v_mov_b32_e32 v119, v0
	v_mov_b32_e32 v72, v0
	v_mov_b32_e32 v73, v0
	v_mov_b32_e32 v74, v0
	v_mov_b32_e32 v75, v0
	v_mov_b32_e32 v76, v0
	v_mov_b32_e32 v77, v0
	v_mov_b32_e32 v78, v0
	v_mov_b32_e32 v79, v0
	v_mov_b32_e32 v88, v0
	v_mov_b32_e32 v89, v0
	v_mov_b32_e32 v90, v0
	v_mov_b32_e32 v91, v0
	v_mov_b32_e32 v92, v0
	v_mov_b32_e32 v93, v0
	v_mov_b32_e32 v94, v0
	v_mov_b32_e32 v95, v0
	v_mov_b32_e32 v104, v0
	v_mov_b32_e32 v105, v0
	v_mov_b32_e32 v106, v0
	v_mov_b32_e32 v107, v0
	v_mov_b32_e32 v108, v0
	v_mov_b32_e32 v109, v0
	v_mov_b32_e32 v110, v0
	v_mov_b32_e32 v111, v0
	v_mov_b32_e32 v120, v0
	v_mov_b32_e32 v121, v0
	v_mov_b32_e32 v122, v0
	v_mov_b32_e32 v123, v0
	v_mov_b32_e32 v124, v0
	v_mov_b32_e32 v125, v0
	v_mov_b32_e32 v126, v0
	v_mov_b32_e32 v127, v0
	v_add_u32_e32 v204, 0x80, v128
	v_add_u32_e32 v205, 0x80, v130
	v_add_u32_e32 v220, 0x80, v132
	v_add_u32_e32 v221, 0x80, v134
	.p2align	3
	s_nop 0

.LBB0_3040:
	s_ashr_i32 s29, s28, 31
	s_lshl_b64 s[30:31], s[28:29], 19
	s_add_u32 s30, s8, s30
	s_addc_u32 s31, s9, s31
	s_and_b64 s[34:35], s[6:7], exec
	s_cselect_b32 s3, s31, s39
	s_cselect_b32 s29, s30, s38
	s_ashr_i32 s27, s26, 31
	s_lshl_b64 s[34:35], s[26:27], 19
	s_add_u32 s34, s43, s34
	s_addc_u32 s35, s44, s35
	s_and_b64 s[40:41], s[6:7], exec
	s_cselect_b32 s27, s35, s37
	s_cselect_b32 s58, s34, s36
	s_add_u32 s59, s36, 0x100
	s_addc_u32 s60, s37, 0
	s_add_u32 s36, s38, 0x40080
	v_mov_b32_e32 v0, 0
	s_addc_u32 s37, s39, 0
	s_mov_b32 s61, -2
	v_mov_b32_e32 v1, v0
	v_mov_b32_e32 v2, v0
	v_mov_b32_e32 v3, v0
	v_mov_b32_e32 v4, v0
	v_mov_b32_e32 v5, v0
	v_mov_b32_e32 v6, v0
	v_mov_b32_e32 v7, v0
	v_mov_b32_e32 v16, v0
	v_mov_b32_e32 v17, v0
	v_mov_b32_e32 v18, v0
	v_mov_b32_e32 v19, v0
	v_mov_b32_e32 v20, v0
	v_mov_b32_e32 v21, v0
	v_mov_b32_e32 v22, v0
	v_mov_b32_e32 v23, v0
	v_mov_b32_e32 v32, v0
	v_mov_b32_e32 v33, v0
	v_mov_b32_e32 v34, v0
	v_mov_b32_e32 v35, v0
	v_mov_b32_e32 v36, v0
	v_mov_b32_e32 v37, v0
	v_mov_b32_e32 v38, v0
	v_mov_b32_e32 v39, v0
	v_mov_b32_e32 v48, v0
	v_mov_b32_e32 v49, v0
	v_mov_b32_e32 v50, v0
	v_mov_b32_e32 v51, v0
	v_mov_b32_e32 v52, v0
	v_mov_b32_e32 v53, v0
	v_mov_b32_e32 v54, v0
	v_mov_b32_e32 v55, v0
	v_mov_b32_e32 v8, v0
	v_mov_b32_e32 v9, v0
	v_mov_b32_e32 v10, v0
	v_mov_b32_e32 v11, v0
	v_mov_b32_e32 v12, v0
	v_mov_b32_e32 v13, v0
	v_mov_b32_e32 v14, v0
	v_mov_b32_e32 v15, v0
	v_mov_b32_e32 v24, v0
	v_mov_b32_e32 v25, v0
	v_mov_b32_e32 v26, v0
	v_mov_b32_e32 v27, v0
	v_mov_b32_e32 v28, v0
	v_mov_b32_e32 v29, v0
	v_mov_b32_e32 v30, v0
	v_mov_b32_e32 v31, v0
	v_mov_b32_e32 v40, v0
	v_mov_b32_e32 v41, v0
	v_mov_b32_e32 v42, v0
	v_mov_b32_e32 v43, v0
	v_mov_b32_e32 v44, v0
	v_mov_b32_e32 v45, v0
	v_mov_b32_e32 v46, v0
	v_mov_b32_e32 v47, v0
	v_mov_b32_e32 v56, v0
	v_mov_b32_e32 v57, v0
	v_mov_b32_e32 v58, v0
	v_mov_b32_e32 v59, v0
	v_mov_b32_e32 v60, v0
	v_mov_b32_e32 v61, v0
	v_mov_b32_e32 v62, v0
	v_mov_b32_e32 v63, v0
	v_mov_b32_e32 v64, v0
	v_mov_b32_e32 v65, v0
	v_mov_b32_e32 v66, v0
	v_mov_b32_e32 v67, v0
	v_mov_b32_e32 v68, v0
	v_mov_b32_e32 v69, v0
	v_mov_b32_e32 v70, v0
	v_mov_b32_e32 v71, v0
	v_mov_b32_e32 v80, v0
	v_mov_b32_e32 v81, v0
	v_mov_b32_e32 v82, v0
	v_mov_b32_e32 v83, v0
	v_mov_b32_e32 v84, v0
	v_mov_b32_e32 v85, v0
	v_mov_b32_e32 v86, v0
	v_mov_b32_e32 v87, v0
	v_mov_b32_e32 v96, v0
	v_mov_b32_e32 v97, v0
	v_mov_b32_e32 v98, v0
	v_mov_b32_e32 v99, v0
	v_mov_b32_e32 v100, v0
	v_mov_b32_e32 v101, v0
	v_mov_b32_e32 v102, v0
	v_mov_b32_e32 v103, v0
	v_mov_b32_e32 v112, v0
	v_mov_b32_e32 v113, v0
	v_mov_b32_e32 v114, v0
	v_mov_b32_e32 v115, v0
	v_mov_b32_e32 v116, v0
	v_mov_b32_e32 v117, v0
	v_mov_b32_e32 v118, v0
	v_mov_b32_e32 v119, v0
	v_mov_b32_e32 v72, v0
	v_mov_b32_e32 v73, v0
	v_mov_b32_e32 v74, v0
	v_mov_b32_e32 v75, v0
	v_mov_b32_e32 v76, v0
	v_mov_b32_e32 v77, v0
	v_mov_b32_e32 v78, v0
	v_mov_b32_e32 v79, v0
	v_mov_b32_e32 v88, v0
	v_mov_b32_e32 v89, v0
	v_mov_b32_e32 v90, v0
	v_mov_b32_e32 v91, v0
	v_mov_b32_e32 v92, v0
	v_mov_b32_e32 v93, v0
	v_mov_b32_e32 v94, v0
	v_mov_b32_e32 v95, v0
	v_mov_b32_e32 v104, v0
	v_mov_b32_e32 v105, v0
	v_mov_b32_e32 v106, v0
	v_mov_b32_e32 v107, v0
	v_mov_b32_e32 v108, v0
	v_mov_b32_e32 v109, v0
	v_mov_b32_e32 v110, v0
	v_mov_b32_e32 v111, v0
	v_mov_b32_e32 v120, v0
	v_mov_b32_e32 v121, v0
	v_mov_b32_e32 v122, v0
	v_mov_b32_e32 v123, v0
	v_mov_b32_e32 v124, v0
	v_mov_b32_e32 v125, v0
	v_mov_b32_e32 v126, v0
	v_mov_b32_e32 v127, v0
	v_add_u32_e32 v204, 0x80, v128
	v_add_u32_e32 v205, 0x80, v130
	.p2align	3
	s_nop 0
